# GEMM1 merge-gate epilogue: bias rows loaded once per 128-feature half and reused across the four token groups (24 fewer loads per tile)
# speedup vs baseline: 1.0036x; 1.0036x over previous
; __device__ __forceinline__ float sigmoid_f(float v) { return __builtin_amdgcn_rcpf(1.f + __builtin_amdgcn_exp2f(-LOG2E * v)); }
; #define LAS __attribute__((address_space(3)))
; __device__ __forceinline__ void phase_gemm1(const Params& p, int layer, LAS unsigned char* lds) {
;     ...
;                         if (type == 4) {
;                             const float* bm = p.b_mg + layer * 3072 + (col0 - INW);
; #pragma unroll
;                             for (int m = 0; m < 4; m++) {
;                                 const float4 b4 = *(const float4*)(bm + m * 16 + fq * 4);
;                                 v[m][0] = sigmoid_f(v[m][0] + b4.x); v[m][1] = sigmoid_f(v[m][1] + b4.y);
;                                 v[m][2] = sigmoid_f(v[m][2] + b4.z); v[m][3] = sigmoid_f(v[m][3] + b4.w);
;                             }
;                         }
;                         if (type == 4) {
;                             LAS unsigned char* srow = lds + wid * 9216 + ((bj * 2 + n) * 16 + fr) * 80 + fq * 4;
; #pragma unroll
;                             for (int m = 0; m < 4; m++) {
;                                 const unsigned q0 = (unsigned)fmaxf(__builtin_rintf(v[m][0] * 255.f), 1.f), q1 = (unsigned)fmaxf(__builtin_rintf(v[m][1] * 255.f), 1.f);
;                                 const unsigned q2 = (unsigned)fmaxf(__builtin_rintf(v[m][2] * 255.f), 1.f), q3 = (unsigned)fmaxf(__builtin_rintf(v[m][3] * 255.f), 1.f);
;                                 *(LAS unsigned*)(srow + m * 16) = q0 | (q1 << 8) | (q2 << 16) | (q3 << 24);
;                             }
.LBB0_257:
	v_add_u32_e32 v145, s92, v131
	s_andn2_b64 vcc, exec, s[4:5]
	s_movk_i32 s4, 0x50
	s_ashr_i32 s67, s66, 31
	v_mad_u32_u24 v135, v143, s4, v145
	s_cbranch_vccnz .LBB0_259
	s_lshl_b64 s[4:5], s[66:67], 2
	s_add_u32 s4, s74, s4
	s_addc_u32 s5, s69, s5
	v_mov_b32_e32 v131, v1
	v_lshl_add_u64 v[138:139], s[4:5], 0, v[130:131]
	s_movk_i32 s4, 0xb800
	s_mov_b32 s5, -1
	v_lshl_add_u64 v[132:133], v[138:139], 0, s[4:5]
	v_add_co_u32_e32 v138, vcc, 0xffffc000, v138
	s_nop 1
	v_addc_co_u32_e32 v139, vcc, -1, v139, vcc
	global_load_dwordx4 v[192:195], v[138:139], off offset:-2048
	global_load_dwordx4 v[196:199], v[132:133], off offset:64
	global_load_dwordx4 v[200:203], v[132:133], off offset:128
	global_load_dwordx4 v[204:207], v[132:133], off offset:192
	s_waitcnt vmcnt(3)
	v_add_f32_e32 v0, v126, v192
	v_mul_f32_e32 v0, 0xbfb8aa3b, v0
	v_exp_f32_e32 v0, v0
	v_add_f32_e32 v126, v129, v195
	v_mul_f32_e32 v126, 0xbfb8aa3b, v126
	v_exp_f32_e32 v126, v126
	v_add_f32_e32 v0, 1.0, v0
	v_rcp_f32_e32 v131, v0
	v_add_f32_e32 v0, v127, v193
	v_mul_f32_e32 v0, 0xbfb8aa3b, v0
	v_exp_f32_e32 v0, v0
	v_add_f32_e32 v126, 1.0, v126
	v_rcp_f32_e32 v126, v126
	v_add_f32_e32 v0, 1.0, v0
	v_rcp_f32_e32 v127, v0
	v_add_f32_e32 v0, v128, v194
	v_mul_f32_e32 v0, 0xbfb8aa3b, v0
	v_exp_f32_e32 v0, v0
	v_mul_f32_e32 v128, 0x437f0000, v131
	v_mul_f32_e32 v127, 0x437f0000, v127
	v_rndne_f32_e32 v128, v128
	v_add_f32_e32 v0, 1.0, v0
	v_rcp_f32_e32 v0, v0
	v_rndne_f32_e32 v127, v127
	v_mul_f32_e32 v126, 0x437f0000, v126
	v_max_f32_e32 v128, 1.0, v128
	v_mul_f32_e32 v0, 0x437f0000, v0
	v_max_f32_e32 v127, 1.0, v127
	v_rndne_f32_e32 v0, v0
	v_rndne_f32_e32 v126, v126
	v_cvt_u32_f32_e32 v128, v128
	v_cvt_u32_f32_e32 v127, v127
	v_max_f32_e32 v0, 1.0, v0
	v_max_f32_e32 v126, 1.0, v126
	v_cvt_u32_f32_sdwa v0, v0 dst_sel:WORD_1 dst_unused:UNUSED_PAD src0_sel:DWORD
	v_cvt_u32_f32_sdwa v126, v126 dst_sel:BYTE_3 dst_unused:UNUSED_PAD src0_sel:DWORD
	v_lshl_or_b32 v127, v127, 8, v128
	v_or3_b32 v0, v127, v0, v126
	s_waitcnt vmcnt(2)
	v_add_f32_e32 v122, v122, v196
	v_add_f32_e32 v123, v123, v197
	v_add_f32_e32 v124, v124, v198
	v_add_f32_e32 v125, v125, v199
	v_mul_f32_e32 v122, 0xbfb8aa3b, v122
	v_mul_f32_e32 v123, 0xbfb8aa3b, v123
	v_exp_f32_e32 v122, v122
	v_exp_f32_e32 v123, v123
	v_mul_f32_e32 v124, 0xbfb8aa3b, v124
	v_mul_f32_e32 v125, 0xbfb8aa3b, v125
	v_exp_f32_e32 v124, v124
	v_exp_f32_e32 v125, v125
	v_add_f32_e32 v122, 1.0, v122
	v_add_f32_e32 v123, 1.0, v123
	v_rcp_f32_e32 v122, v122
	v_rcp_f32_e32 v123, v123
	v_add_f32_e32 v124, 1.0, v124
	v_add_f32_e32 v125, 1.0, v125
	v_rcp_f32_e32 v124, v124
	v_rcp_f32_e32 v125, v125
	v_mul_f32_e32 v122, 0x437f0000, v122
	v_mul_f32_e32 v123, 0x437f0000, v123
	v_rndne_f32_e32 v122, v122
	v_rndne_f32_e32 v123, v123
	v_mul_f32_e32 v124, 0x437f0000, v124
	v_mul_f32_e32 v125, 0x437f0000, v125
	v_max_f32_e32 v122, 1.0, v122
	v_max_f32_e32 v123, 1.0, v123
	v_rndne_f32_e32 v124, v124
	v_rndne_f32_e32 v125, v125
	v_cvt_u32_f32_e32 v122, v122
	v_cvt_u32_f32_e32 v123, v123
	v_max_f32_e32 v124, 1.0, v124
	v_max_f32_e32 v125, 1.0, v125
	v_cvt_u32_f32_sdwa v124, v124 dst_sel:WORD_1 dst_unused:UNUSED_PAD src0_sel:DWORD
	v_cvt_u32_f32_sdwa v125, v125 dst_sel:BYTE_3 dst_unused:UNUSED_PAD src0_sel:DWORD
	v_lshl_or_b32 v122, v123, 8, v122
	v_or3_b32 v122, v122, v124, v125
	ds_write2_b32 v135, v0, v122 offset1:4
	s_waitcnt vmcnt(1)
	v_add_f32_e32 v118, v118, v200
	v_add_f32_e32 v119, v119, v201
	v_add_f32_e32 v120, v120, v202
	v_add_f32_e32 v121, v121, v203
	v_mul_f32_e32 v118, 0xbfb8aa3b, v118
	v_mul_f32_e32 v119, 0xbfb8aa3b, v119
	v_exp_f32_e32 v118, v118
	v_exp_f32_e32 v119, v119
	v_mul_f32_e32 v120, 0xbfb8aa3b, v120
	v_mul_f32_e32 v121, 0xbfb8aa3b, v121
	v_exp_f32_e32 v120, v120
	v_exp_f32_e32 v121, v121
	v_add_f32_e32 v118, 1.0, v118
	v_add_f32_e32 v119, 1.0, v119
	v_rcp_f32_e32 v118, v118
	v_rcp_f32_e32 v119, v119
	v_add_f32_e32 v120, 1.0, v120
	v_add_f32_e32 v121, 1.0, v121
	v_rcp_f32_e32 v120, v120
	v_rcp_f32_e32 v121, v121
	v_mul_f32_e32 v0, 0x437f0000, v118
	v_mul_f32_e32 v118, 0x437f0000, v119
	v_rndne_f32_e32 v0, v0
	v_rndne_f32_e32 v118, v118
	v_mul_f32_e32 v119, 0x437f0000, v120
	v_mul_f32_e32 v120, 0x437f0000, v121
	v_max_f32_e32 v0, 1.0, v0
	v_max_f32_e32 v118, 1.0, v118
	v_rndne_f32_e32 v119, v119
	v_rndne_f32_e32 v120, v120
	v_cvt_u32_f32_e32 v0, v0
	v_cvt_u32_f32_e32 v118, v118
	v_max_f32_e32 v119, 1.0, v119
	v_max_f32_e32 v120, 1.0, v120
	v_cvt_u32_f32_sdwa v119, v119 dst_sel:WORD_1 dst_unused:UNUSED_PAD src0_sel:DWORD
	v_cvt_u32_f32_sdwa v120, v120 dst_sel:BYTE_3 dst_unused:UNUSED_PAD src0_sel:DWORD
	v_lshl_or_b32 v0, v118, 8, v0
	v_or3_b32 v0, v0, v119, v120
	s_waitcnt vmcnt(0)
	v_add_f32_e32 v114, v114, v204
	v_add_f32_e32 v115, v115, v205
	v_mul_f32_e32 v114, 0xbfb8aa3b, v114
	v_mul_f32_e32 v115, 0xbfb8aa3b, v115
	v_add_f32_e32 v116, v116, v206
	v_add_f32_e32 v117, v117, v207
	v_exp_f32_e32 v114, v114
	v_exp_f32_e32 v115, v115
	v_mul_f32_e32 v116, 0xbfb8aa3b, v116
	v_mul_f32_e32 v117, 0xbfb8aa3b, v117
	v_exp_f32_e32 v116, v116
	v_exp_f32_e32 v117, v117
	v_add_f32_e32 v114, 1.0, v114
	v_add_f32_e32 v115, 1.0, v115
	v_rcp_f32_e32 v114, v114
	v_rcp_f32_e32 v115, v115
	v_add_f32_e32 v116, 1.0, v116
	v_add_f32_e32 v117, 1.0, v117
	v_rcp_f32_e32 v116, v116
	v_rcp_f32_e32 v117, v117
	v_mul_f32_e32 v114, 0x437f0000, v114
	v_mul_f32_e32 v115, 0x437f0000, v115
	v_rndne_f32_e32 v114, v114
	v_rndne_f32_e32 v115, v115
	v_mul_f32_e32 v116, 0x437f0000, v116
	v_mul_f32_e32 v117, 0x437f0000, v117
	v_max_f32_e32 v114, 1.0, v114
	v_max_f32_e32 v115, 1.0, v115
	v_rndne_f32_e32 v116, v116
	v_rndne_f32_e32 v117, v117
	v_cvt_u32_f32_e32 v114, v114
	v_cvt_u32_f32_e32 v115, v115
	v_max_f32_e32 v116, 1.0, v116
	v_max_f32_e32 v117, 1.0, v117
	v_cvt_u32_f32_sdwa v116, v116 dst_sel:WORD_1 dst_unused:UNUSED_PAD src0_sel:DWORD
	v_cvt_u32_f32_sdwa v117, v117 dst_sel:BYTE_3 dst_unused:UNUSED_PAD src0_sel:DWORD
	v_lshl_or_b32 v114, v115, 8, v114
	v_or3_b32 v114, v114, v116, v117
	ds_write2_b32 v135, v0, v114 offset0:8 offset1:12

; __device__ __forceinline__ float sigmoid_f(float v) { return __builtin_amdgcn_rcpf(1.f + __builtin_amdgcn_exp2f(-LOG2E * v)); }
; #define LAS __attribute__((address_space(3)))
; __device__ __forceinline__ void phase_gemm1(const Params& p, int layer, LAS unsigned char* lds) {
;     ...
;                         if (type == 4) {
;                             const float* bm = p.b_mg + layer * 3072 + (col0 - INW);
; #pragma unroll
;                             for (int m = 0; m < 4; m++) {
;                                 const float4 b4 = *(const float4*)(bm + m * 16 + fq * 4);
;                                 v[m][0] = sigmoid_f(v[m][0] + b4.x); v[m][1] = sigmoid_f(v[m][1] + b4.y);
;                                 v[m][2] = sigmoid_f(v[m][2] + b4.z); v[m][3] = sigmoid_f(v[m][3] + b4.w);
;                             }
;                         }
;                         if (type == 4) {
;                             LAS unsigned char* srow = lds + wid * 9216 + ((bj * 2 + n) * 16 + fr) * 80 + fq * 4;
; #pragma unroll
;                             for (int m = 0; m < 4; m++) {
;                                 const unsigned q0 = (unsigned)fmaxf(__builtin_rintf(v[m][0] * 255.f), 1.f), q1 = (unsigned)fmaxf(__builtin_rintf(v[m][1] * 255.f), 1.f);
;                                 const unsigned q2 = (unsigned)fmaxf(__builtin_rintf(v[m][2] * 255.f), 1.f), q3 = (unsigned)fmaxf(__builtin_rintf(v[m][3] * 255.f), 1.f);
;                                 *(LAS unsigned*)(srow + m * 16) = q0 | (q1 << 8) | (q2 << 16) | (q3 << 24);
;                             }
.LBB0_275:
	s_movk_i32 s16, 0x50
	s_andn2_b64 vcc, exec, s[74:75]
	v_mad_u32_u24 v100, v0, s16, v145
	v_readlane_b32 s74, v252, 16
	s_mov_b32 s69, s68
	s_cbranch_vccnz .LBB0_277
	s_lshl_b64 s[16:17], s[66:67], 2
	s_add_u32 s16, s74, s16
	s_addc_u32 s17, s69, s17
	v_mov_b32_e32 v131, v1
	v_lshl_add_u64 v[104:105], s[16:17], 0, v[130:131]
	s_movk_i32 s16, 0xb800
	s_mov_b32 s17, -1
	v_lshl_add_u64 v[98:99], v[104:105], 0, s[16:17]
	v_add_co_u32_e32 v104, vcc, 0xffffc000, v104
	s_nop 1
	v_addc_co_u32_e32 v105, vcc, -1, v105, vcc
	v_add_f32_e32 v0, v94, v192
	v_mul_f32_e32 v0, 0xbfb8aa3b, v0
	v_exp_f32_e32 v0, v0
	v_add_f32_e32 v94, v97, v195
	v_mul_f32_e32 v94, 0xbfb8aa3b, v94
	v_exp_f32_e32 v94, v94
	v_add_f32_e32 v0, 1.0, v0
	v_rcp_f32_e32 v104, v0
	v_add_f32_e32 v0, v95, v193
	v_mul_f32_e32 v0, 0xbfb8aa3b, v0
	v_exp_f32_e32 v0, v0
	v_add_f32_e32 v94, 1.0, v94
	v_rcp_f32_e32 v94, v94
	v_add_f32_e32 v0, 1.0, v0
	v_rcp_f32_e32 v95, v0
	v_add_f32_e32 v0, v96, v194
	v_mul_f32_e32 v0, 0xbfb8aa3b, v0
	v_exp_f32_e32 v0, v0
	v_mul_f32_e32 v95, 0x437f0000, v95
	v_rndne_f32_e32 v95, v95
	v_mul_f32_e32 v94, 0x437f0000, v94
	v_add_f32_e32 v0, 1.0, v0
	v_rcp_f32_e32 v0, v0
	v_max_f32_e32 v95, 1.0, v95
	v_rndne_f32_e32 v94, v94
	v_cvt_u32_f32_e32 v95, v95
	v_mul_f32_e32 v0, 0x437f0000, v0
	v_rndne_f32_e32 v0, v0
	v_max_f32_e32 v0, 1.0, v0
	v_max_f32_e32 v94, 1.0, v94
	v_cvt_u32_f32_sdwa v0, v0 dst_sel:WORD_1 dst_unused:UNUSED_PAD src0_sel:DWORD
	v_cvt_u32_f32_sdwa v94, v94 dst_sel:BYTE_3 dst_unused:UNUSED_PAD src0_sel:DWORD
	v_add_f32_e32 v90, v90, v196
	v_add_f32_e32 v91, v91, v197
	v_add_f32_e32 v92, v92, v198
	v_add_f32_e32 v93, v93, v199
	v_mul_f32_e32 v90, 0xbfb8aa3b, v90
	v_mul_f32_e32 v91, 0xbfb8aa3b, v91
	v_exp_f32_e32 v90, v90
	v_exp_f32_e32 v91, v91
	v_mul_f32_e32 v92, 0xbfb8aa3b, v92
	v_mul_f32_e32 v93, 0xbfb8aa3b, v93
	v_exp_f32_e32 v92, v92
	v_exp_f32_e32 v93, v93
	v_add_f32_e32 v90, 1.0, v90
	v_add_f32_e32 v91, 1.0, v91
	v_rcp_f32_e32 v90, v90
	v_rcp_f32_e32 v91, v91
	v_add_f32_e32 v92, 1.0, v92
	v_add_f32_e32 v93, 1.0, v93
	v_rcp_f32_e32 v92, v92
	v_rcp_f32_e32 v93, v93
	v_mul_f32_e32 v90, 0x437f0000, v90
	v_mul_f32_e32 v91, 0x437f0000, v91
	v_rndne_f32_e32 v90, v90
	v_rndne_f32_e32 v91, v91
	v_mul_f32_e32 v92, 0x437f0000, v92
	v_mul_f32_e32 v93, 0x437f0000, v93
	v_max_f32_e32 v90, 1.0, v90
	v_max_f32_e32 v91, 1.0, v91
	v_rndne_f32_e32 v92, v92
	v_rndne_f32_e32 v93, v93
	v_cvt_u32_f32_e32 v90, v90
	v_cvt_u32_f32_e32 v91, v91
	v_max_f32_e32 v92, 1.0, v92
	v_max_f32_e32 v93, 1.0, v93
	v_cvt_u32_f32_sdwa v92, v92 dst_sel:WORD_1 dst_unused:UNUSED_PAD src0_sel:DWORD
	v_cvt_u32_f32_sdwa v93, v93 dst_sel:BYTE_3 dst_unused:UNUSED_PAD src0_sel:DWORD
	v_lshl_or_b32 v90, v91, 8, v90
	v_or3_b32 v90, v90, v92, v93
	v_add_f32_e32 v86, v86, v200
	v_add_f32_e32 v87, v87, v201
	v_add_f32_e32 v82, v82, v204
	v_add_f32_e32 v83, v83, v205
	v_mul_f32_e32 v86, 0xbfb8aa3b, v86
	v_mul_f32_e32 v87, 0xbfb8aa3b, v87
	v_add_f32_e32 v88, v88, v202
	v_add_f32_e32 v89, v89, v203
	v_mul_f32_e32 v82, 0xbfb8aa3b, v82
	v_mul_f32_e32 v83, 0xbfb8aa3b, v83
	v_add_f32_e32 v84, v84, v206
	v_add_f32_e32 v85, v85, v207
	v_exp_f32_e32 v86, v86
	v_exp_f32_e32 v87, v87
	v_mul_f32_e32 v88, 0xbfb8aa3b, v88
	v_mul_f32_e32 v89, 0xbfb8aa3b, v89
	v_exp_f32_e32 v82, v82
	v_exp_f32_e32 v83, v83
	v_mul_f32_e32 v84, 0xbfb8aa3b, v84
	v_mul_f32_e32 v85, 0xbfb8aa3b, v85
	v_mul_f32_e32 v96, 0x437f0000, v104
	v_exp_f32_e32 v88, v88
	v_exp_f32_e32 v89, v89
	v_exp_f32_e32 v84, v84
	v_exp_f32_e32 v85, v85
	v_rndne_f32_e32 v96, v96
	v_max_f32_e32 v96, 1.0, v96
	v_cvt_u32_f32_e32 v96, v96
	v_add_f32_e32 v86, 1.0, v86
	v_add_f32_e32 v87, 1.0, v87
	v_add_f32_e32 v82, 1.0, v82
	v_add_f32_e32 v83, 1.0, v83
	v_rcp_f32_e32 v86, v86
	v_rcp_f32_e32 v87, v87
	v_add_f32_e32 v88, 1.0, v88
	v_add_f32_e32 v89, 1.0, v89
	v_rcp_f32_e32 v82, v82
	v_rcp_f32_e32 v83, v83
	v_add_f32_e32 v84, 1.0, v84
	v_add_f32_e32 v85, 1.0, v85
	v_rcp_f32_e32 v88, v88
	v_rcp_f32_e32 v89, v89
	v_rcp_f32_e32 v84, v84
	v_rcp_f32_e32 v85, v85
	v_lshl_or_b32 v95, v95, 8, v96
	v_or3_b32 v0, v95, v0, v94
	ds_write2_b32 v100, v0, v90 offset1:4
	v_mul_f32_e32 v0, 0x437f0000, v86
	v_mul_f32_e32 v86, 0x437f0000, v87
	v_mul_f32_e32 v82, 0x437f0000, v82
	v_mul_f32_e32 v83, 0x437f0000, v83
	v_rndne_f32_e32 v0, v0
	v_rndne_f32_e32 v86, v86
	v_mul_f32_e32 v87, 0x437f0000, v88
	v_mul_f32_e32 v88, 0x437f0000, v89
	v_rndne_f32_e32 v82, v82
	v_rndne_f32_e32 v83, v83
	v_mul_f32_e32 v84, 0x437f0000, v84
	v_mul_f32_e32 v85, 0x437f0000, v85
	v_max_f32_e32 v0, 1.0, v0
	v_max_f32_e32 v86, 1.0, v86
	v_rndne_f32_e32 v87, v87
	v_rndne_f32_e32 v88, v88
	v_max_f32_e32 v82, 1.0, v82
	v_max_f32_e32 v83, 1.0, v83
	v_rndne_f32_e32 v84, v84
	v_rndne_f32_e32 v85, v85
	v_cvt_u32_f32_e32 v0, v0
	v_cvt_u32_f32_e32 v86, v86
	v_max_f32_e32 v87, 1.0, v87
	v_max_f32_e32 v88, 1.0, v88
	v_cvt_u32_f32_e32 v82, v82
	v_cvt_u32_f32_e32 v83, v83
	v_max_f32_e32 v84, 1.0, v84
	v_max_f32_e32 v85, 1.0, v85
	v_cvt_u32_f32_sdwa v87, v87 dst_sel:WORD_1 dst_unused:UNUSED_PAD src0_sel:DWORD
	v_cvt_u32_f32_sdwa v88, v88 dst_sel:BYTE_3 dst_unused:UNUSED_PAD src0_sel:DWORD
	v_cvt_u32_f32_sdwa v84, v84 dst_sel:WORD_1 dst_unused:UNUSED_PAD src0_sel:DWORD
	v_cvt_u32_f32_sdwa v85, v85 dst_sel:BYTE_3 dst_unused:UNUSED_PAD src0_sel:DWORD
	v_lshl_or_b32 v0, v86, 8, v0
	v_lshl_or_b32 v82, v83, 8, v82
	v_or3_b32 v0, v0, v87, v88
	v_or3_b32 v82, v82, v84, v85
	ds_write2_b32 v100, v0, v82 offset0:8 offset1:12

; __device__ __forceinline__ float sigmoid_f(float v) { return __builtin_amdgcn_rcpf(1.f + __builtin_amdgcn_exp2f(-LOG2E * v)); }
; #define LAS __attribute__((address_space(3)))
; __device__ __forceinline__ void phase_gemm1(const Params& p, int layer, LAS unsigned char* lds) {
;     ...
;                         if (type == 4) {
;                             const float* bm = p.b_mg + layer * 3072 + (col0 - INW);
; #pragma unroll
;                             for (int m = 0; m < 4; m++) {
;                                 const float4 b4 = *(const float4*)(bm + m * 16 + fq * 4);
;                                 v[m][0] = sigmoid_f(v[m][0] + b4.x); v[m][1] = sigmoid_f(v[m][1] + b4.y);
;                                 v[m][2] = sigmoid_f(v[m][2] + b4.z); v[m][3] = sigmoid_f(v[m][3] + b4.w);
;                             }
;                         }
;                         if (type == 4) {
;                             LAS unsigned char* srow = lds + wid * 9216 + ((bj * 2 + n) * 16 + fr) * 80 + fq * 4;
; #pragma unroll
;                             for (int m = 0; m < 4; m++) {
;                                 const unsigned q0 = (unsigned)fmaxf(__builtin_rintf(v[m][0] * 255.f), 1.f), q1 = (unsigned)fmaxf(__builtin_rintf(v[m][1] * 255.f), 1.f);
;                                 const unsigned q2 = (unsigned)fmaxf(__builtin_rintf(v[m][2] * 255.f), 1.f), q3 = (unsigned)fmaxf(__builtin_rintf(v[m][3] * 255.f), 1.f);
;                                 *(LAS unsigned*)(srow + m * 16) = q0 | (q1 << 8) | (q2 << 16) | (q3 << 24);
;                             }
.LBB0_284:
	s_lshl_b64 s[10:11], s[66:67], 2
	s_add_u32 s10, s74, s10
	s_addc_u32 s11, s69, s11
	v_mov_b32_e32 v131, v1
	v_lshl_add_u64 v[88:89], s[10:11], 0, v[130:131]
	s_movk_i32 s10, 0xb800
	s_mov_b32 s11, -1
	v_lshl_add_u64 v[82:83], v[88:89], 0, s[10:11]
	v_add_co_u32_e32 v88, vcc, 0xffffc000, v88
	s_nop 1
	v_addc_co_u32_e32 v89, vcc, -1, v89, vcc
	v_add_f32_e32 v0, v78, v192
	v_mul_f32_e32 v0, 0xbfb8aa3b, v0
	v_exp_f32_e32 v0, v0
	v_add_f32_e32 v78, v81, v195
	v_mul_f32_e32 v78, 0xbfb8aa3b, v78
	v_exp_f32_e32 v78, v78
	v_add_f32_e32 v0, 1.0, v0
	v_rcp_f32_e32 v88, v0
	v_add_f32_e32 v0, v79, v193
	v_mul_f32_e32 v0, 0xbfb8aa3b, v0
	v_exp_f32_e32 v0, v0
	v_add_f32_e32 v78, 1.0, v78
	v_rcp_f32_e32 v78, v78
	v_add_f32_e32 v0, 1.0, v0
	v_rcp_f32_e32 v79, v0
	v_add_f32_e32 v0, v80, v194
	v_mul_f32_e32 v0, 0xbfb8aa3b, v0
	v_exp_f32_e32 v0, v0
	v_mul_f32_e32 v79, 0x437f0000, v79
	v_rndne_f32_e32 v79, v79
	v_mul_f32_e32 v78, 0x437f0000, v78
	v_add_f32_e32 v0, 1.0, v0
	v_rcp_f32_e32 v0, v0
	v_max_f32_e32 v79, 1.0, v79
	v_rndne_f32_e32 v78, v78
	v_cvt_u32_f32_e32 v79, v79
	v_mul_f32_e32 v0, 0x437f0000, v0
	v_rndne_f32_e32 v0, v0
	v_max_f32_e32 v0, 1.0, v0
	v_max_f32_e32 v78, 1.0, v78
	v_cvt_u32_f32_sdwa v0, v0 dst_sel:WORD_1 dst_unused:UNUSED_PAD src0_sel:DWORD
	v_cvt_u32_f32_sdwa v78, v78 dst_sel:BYTE_3 dst_unused:UNUSED_PAD src0_sel:DWORD
	v_add_f32_e32 v74, v74, v196
	v_add_f32_e32 v75, v75, v197
	v_add_f32_e32 v76, v76, v198
	v_add_f32_e32 v77, v77, v199
	v_mul_f32_e32 v74, 0xbfb8aa3b, v74
	v_mul_f32_e32 v75, 0xbfb8aa3b, v75
	v_exp_f32_e32 v74, v74
	v_exp_f32_e32 v75, v75
	v_mul_f32_e32 v76, 0xbfb8aa3b, v76
	v_mul_f32_e32 v77, 0xbfb8aa3b, v77
	v_exp_f32_e32 v76, v76
	v_exp_f32_e32 v77, v77
	v_add_f32_e32 v74, 1.0, v74
	v_add_f32_e32 v75, 1.0, v75
	v_rcp_f32_e32 v74, v74
	v_rcp_f32_e32 v75, v75
	v_add_f32_e32 v76, 1.0, v76
	v_add_f32_e32 v77, 1.0, v77
	v_rcp_f32_e32 v76, v76
	v_rcp_f32_e32 v77, v77
	v_mul_f32_e32 v74, 0x437f0000, v74
	v_mul_f32_e32 v75, 0x437f0000, v75
	v_rndne_f32_e32 v74, v74
	v_rndne_f32_e32 v75, v75
	v_mul_f32_e32 v76, 0x437f0000, v76
	v_mul_f32_e32 v77, 0x437f0000, v77
	v_max_f32_e32 v74, 1.0, v74
	v_max_f32_e32 v75, 1.0, v75
	v_rndne_f32_e32 v76, v76
	v_rndne_f32_e32 v77, v77
	v_cvt_u32_f32_e32 v74, v74
	v_cvt_u32_f32_e32 v75, v75
	v_max_f32_e32 v76, 1.0, v76
	v_max_f32_e32 v77, 1.0, v77
	v_cvt_u32_f32_sdwa v76, v76 dst_sel:WORD_1 dst_unused:UNUSED_PAD src0_sel:DWORD
	v_cvt_u32_f32_sdwa v77, v77 dst_sel:BYTE_3 dst_unused:UNUSED_PAD src0_sel:DWORD
	v_lshl_or_b32 v74, v75, 8, v74
	v_or3_b32 v74, v74, v76, v77
	v_add_f32_e32 v70, v70, v200
	v_add_f32_e32 v71, v71, v201
	v_add_f32_e32 v66, v66, v204
	v_add_f32_e32 v67, v67, v205
	v_mul_f32_e32 v70, 0xbfb8aa3b, v70
	v_mul_f32_e32 v71, 0xbfb8aa3b, v71
	v_add_f32_e32 v72, v72, v202
	v_add_f32_e32 v73, v73, v203
	v_mul_f32_e32 v66, 0xbfb8aa3b, v66
	v_mul_f32_e32 v67, 0xbfb8aa3b, v67
	v_add_f32_e32 v68, v68, v206
	v_add_f32_e32 v69, v69, v207
	v_exp_f32_e32 v70, v70
	v_exp_f32_e32 v71, v71
	v_mul_f32_e32 v72, 0xbfb8aa3b, v72
	v_mul_f32_e32 v73, 0xbfb8aa3b, v73
	v_exp_f32_e32 v66, v66
	v_exp_f32_e32 v67, v67
	v_mul_f32_e32 v68, 0xbfb8aa3b, v68
	v_mul_f32_e32 v69, 0xbfb8aa3b, v69
	v_mul_f32_e32 v80, 0x437f0000, v88
	v_exp_f32_e32 v72, v72
	v_exp_f32_e32 v73, v73
	v_exp_f32_e32 v68, v68
	v_exp_f32_e32 v69, v69
	v_rndne_f32_e32 v80, v80
	v_max_f32_e32 v80, 1.0, v80
	v_cvt_u32_f32_e32 v80, v80
	v_add_f32_e32 v70, 1.0, v70
	v_add_f32_e32 v71, 1.0, v71
	v_add_f32_e32 v66, 1.0, v66
	v_add_f32_e32 v67, 1.0, v67
	v_rcp_f32_e32 v70, v70
	v_rcp_f32_e32 v71, v71
	v_add_f32_e32 v72, 1.0, v72
	v_add_f32_e32 v73, 1.0, v73
	v_rcp_f32_e32 v66, v66
	v_rcp_f32_e32 v67, v67
	v_add_f32_e32 v68, 1.0, v68
	v_add_f32_e32 v69, 1.0, v69
	v_rcp_f32_e32 v72, v72
	v_rcp_f32_e32 v73, v73
	v_rcp_f32_e32 v68, v68
	v_rcp_f32_e32 v69, v69
	v_lshl_or_b32 v79, v79, 8, v80
	v_or3_b32 v0, v79, v0, v78
	ds_write2_b32 v84, v0, v74 offset0:192 offset1:196
	v_mul_f32_e32 v0, 0x437f0000, v70
	v_mul_f32_e32 v70, 0x437f0000, v71
	v_mul_f32_e32 v66, 0x437f0000, v66
	v_mul_f32_e32 v67, 0x437f0000, v67
	v_rndne_f32_e32 v0, v0
	v_rndne_f32_e32 v70, v70
	v_mul_f32_e32 v71, 0x437f0000, v72
	v_mul_f32_e32 v72, 0x437f0000, v73
	v_rndne_f32_e32 v66, v66
	v_rndne_f32_e32 v67, v67
	v_mul_f32_e32 v68, 0x437f0000, v68
	v_mul_f32_e32 v69, 0x437f0000, v69
	v_max_f32_e32 v0, 1.0, v0
	v_max_f32_e32 v70, 1.0, v70
	v_rndne_f32_e32 v71, v71
	v_rndne_f32_e32 v72, v72
	v_max_f32_e32 v66, 1.0, v66
	v_max_f32_e32 v67, 1.0, v67
	v_rndne_f32_e32 v68, v68
	v_rndne_f32_e32 v69, v69
	v_cvt_u32_f32_e32 v0, v0
	v_cvt_u32_f32_e32 v70, v70
	v_max_f32_e32 v71, 1.0, v71
	v_max_f32_e32 v72, 1.0, v72
	v_cvt_u32_f32_e32 v66, v66
	v_cvt_u32_f32_e32 v67, v67
	v_max_f32_e32 v68, 1.0, v68
	v_max_f32_e32 v69, 1.0, v69
	v_cvt_u32_f32_sdwa v71, v71 dst_sel:WORD_1 dst_unused:UNUSED_PAD src0_sel:DWORD
	v_cvt_u32_f32_sdwa v72, v72 dst_sel:BYTE_3 dst_unused:UNUSED_PAD src0_sel:DWORD
	v_cvt_u32_f32_sdwa v68, v68 dst_sel:WORD_1 dst_unused:UNUSED_PAD src0_sel:DWORD
	v_cvt_u32_f32_sdwa v69, v69 dst_sel:BYTE_3 dst_unused:UNUSED_PAD src0_sel:DWORD
	v_lshl_or_b32 v0, v70, 8, v0
	v_lshl_or_b32 v66, v67, 8, v66
	v_or3_b32 v0, v0, v71, v72
	v_or3_b32 v66, v66, v68, v69
	ds_write2_b32 v84, v0, v66 offset0:200 offset1:204

; __device__ __forceinline__ float sigmoid_f(float v) { return __builtin_amdgcn_rcpf(1.f + __builtin_amdgcn_exp2f(-LOG2E * v)); }
; #define LAS __attribute__((address_space(3)))
; __device__ __forceinline__ void phase_gemm1(const Params& p, int layer, LAS unsigned char* lds) {
;     ...
;                         if (type == 4) {
;                             const float* bm = p.b_mg + layer * 3072 + (col0 - INW);
; #pragma unroll
;                             for (int m = 0; m < 4; m++) {
;                                 const float4 b4 = *(const float4*)(bm + m * 16 + fq * 4);
;                                 v[m][0] = sigmoid_f(v[m][0] + b4.x); v[m][1] = sigmoid_f(v[m][1] + b4.y);
;                                 v[m][2] = sigmoid_f(v[m][2] + b4.z); v[m][3] = sigmoid_f(v[m][3] + b4.w);
;                             }
;                         }
;                         if (type == 4) {
;                             LAS unsigned char* srow = lds + wid * 9216 + ((bj * 2 + n) * 16 + fr) * 80 + fq * 4;
; #pragma unroll
;                             for (int m = 0; m < 4; m++) {
;                                 const unsigned q0 = (unsigned)fmaxf(__builtin_rintf(v[m][0] * 255.f), 1.f), q1 = (unsigned)fmaxf(__builtin_rintf(v[m][1] * 255.f), 1.f);
;                                 const unsigned q2 = (unsigned)fmaxf(__builtin_rintf(v[m][2] * 255.f), 1.f), q3 = (unsigned)fmaxf(__builtin_rintf(v[m][3] * 255.f), 1.f);
;                                 *(LAS unsigned*)(srow + m * 16) = q0 | (q1 << 8) | (q2 << 16) | (q3 << 24);
;                             }
.LBB0_292:
	s_lshl_b64 s[6:7], s[66:67], 2
	s_add_u32 s6, s74, s6
	s_addc_u32 s7, s69, s7
	v_mov_b32_e32 v131, v1
	v_lshl_add_u64 v[120:121], s[6:7], 0, v[130:131]
	s_movk_i32 s6, 0xb800
	s_mov_b32 s7, -1
	v_lshl_add_u64 v[114:115], v[120:121], 0, s[6:7]
	v_add_co_u32_e32 v120, vcc, 0xffffc000, v120
	s_nop 1
	v_addc_co_u32_e32 v121, vcc, -1, v121, vcc
	v_add_f32_e32 v0, v110, v192
	v_mul_f32_e32 v0, 0xbfb8aa3b, v0
	v_exp_f32_e32 v0, v0
	v_add_f32_e32 v110, v113, v195
	v_mul_f32_e32 v110, 0xbfb8aa3b, v110
	v_exp_f32_e32 v110, v110
	v_add_f32_e32 v0, 1.0, v0
	v_rcp_f32_e32 v120, v0
	v_add_f32_e32 v0, v111, v193
	v_mul_f32_e32 v0, 0xbfb8aa3b, v0
	v_exp_f32_e32 v0, v0
	v_add_f32_e32 v110, 1.0, v110
	v_rcp_f32_e32 v110, v110
	v_add_f32_e32 v0, 1.0, v0
	v_rcp_f32_e32 v111, v0
	v_add_f32_e32 v0, v112, v194
	v_mul_f32_e32 v0, 0xbfb8aa3b, v0
	v_exp_f32_e32 v0, v0
	v_mul_f32_e32 v111, 0x437f0000, v111
	v_rndne_f32_e32 v111, v111
	v_mul_f32_e32 v110, 0x437f0000, v110
	v_add_f32_e32 v0, 1.0, v0
	v_rcp_f32_e32 v0, v0
	v_max_f32_e32 v111, 1.0, v111
	v_rndne_f32_e32 v110, v110
	v_cvt_u32_f32_e32 v111, v111
	v_mul_f32_e32 v0, 0x437f0000, v0
	v_rndne_f32_e32 v0, v0
	v_max_f32_e32 v0, 1.0, v0
	v_max_f32_e32 v110, 1.0, v110
	v_cvt_u32_f32_sdwa v0, v0 dst_sel:WORD_1 dst_unused:UNUSED_PAD src0_sel:DWORD
	v_cvt_u32_f32_sdwa v110, v110 dst_sel:BYTE_3 dst_unused:UNUSED_PAD src0_sel:DWORD
	v_add_f32_e32 v106, v106, v196
	v_add_f32_e32 v107, v107, v197
	v_add_f32_e32 v108, v108, v198
	v_add_f32_e32 v109, v109, v199
	v_mul_f32_e32 v106, 0xbfb8aa3b, v106
	v_mul_f32_e32 v107, 0xbfb8aa3b, v107
	v_exp_f32_e32 v106, v106
	v_exp_f32_e32 v107, v107
	v_mul_f32_e32 v108, 0xbfb8aa3b, v108
	v_mul_f32_e32 v109, 0xbfb8aa3b, v109
	v_exp_f32_e32 v108, v108
	v_exp_f32_e32 v109, v109
	v_add_f32_e32 v106, 1.0, v106
	v_add_f32_e32 v107, 1.0, v107
	v_rcp_f32_e32 v106, v106
	v_rcp_f32_e32 v107, v107
	v_add_f32_e32 v108, 1.0, v108
	v_add_f32_e32 v109, 1.0, v109
	v_rcp_f32_e32 v108, v108
	v_rcp_f32_e32 v109, v109
	v_mul_f32_e32 v106, 0x437f0000, v106
	v_mul_f32_e32 v107, 0x437f0000, v107
	v_rndne_f32_e32 v106, v106
	v_rndne_f32_e32 v107, v107
	v_mul_f32_e32 v108, 0x437f0000, v108
	v_mul_f32_e32 v109, 0x437f0000, v109
	v_max_f32_e32 v106, 1.0, v106
	v_max_f32_e32 v107, 1.0, v107
	v_rndne_f32_e32 v108, v108
	v_rndne_f32_e32 v109, v109
	v_cvt_u32_f32_e32 v106, v106
	v_cvt_u32_f32_e32 v107, v107
	v_max_f32_e32 v108, 1.0, v108
	v_max_f32_e32 v109, 1.0, v109
	v_cvt_u32_f32_sdwa v108, v108 dst_sel:WORD_1 dst_unused:UNUSED_PAD src0_sel:DWORD
	v_cvt_u32_f32_sdwa v109, v109 dst_sel:BYTE_3 dst_unused:UNUSED_PAD src0_sel:DWORD
	v_lshl_or_b32 v106, v107, 8, v106
	v_or3_b32 v106, v106, v108, v109
	v_add_f32_e32 v102, v102, v200
	v_add_f32_e32 v103, v103, v201
	v_add_f32_e32 v98, v98, v204
	v_add_f32_e32 v99, v99, v205
	v_mul_f32_e32 v102, 0xbfb8aa3b, v102
	v_mul_f32_e32 v103, 0xbfb8aa3b, v103
	v_add_f32_e32 v104, v104, v202
	v_add_f32_e32 v105, v105, v203
	v_mul_f32_e32 v98, 0xbfb8aa3b, v98
	v_mul_f32_e32 v99, 0xbfb8aa3b, v99
	v_add_f32_e32 v100, v100, v206
	v_add_f32_e32 v101, v101, v207
	v_exp_f32_e32 v102, v102
	v_exp_f32_e32 v103, v103
	v_mul_f32_e32 v104, 0xbfb8aa3b, v104
	v_mul_f32_e32 v105, 0xbfb8aa3b, v105
	v_exp_f32_e32 v98, v98
	v_exp_f32_e32 v99, v99
	v_mul_f32_e32 v100, 0xbfb8aa3b, v100
	v_mul_f32_e32 v101, 0xbfb8aa3b, v101
	v_mul_f32_e32 v112, 0x437f0000, v120
	v_exp_f32_e32 v104, v104
	v_exp_f32_e32 v105, v105
	v_exp_f32_e32 v100, v100
	v_exp_f32_e32 v101, v101
	v_rndne_f32_e32 v112, v112
	v_max_f32_e32 v112, 1.0, v112
	v_cvt_u32_f32_e32 v112, v112
	v_add_f32_e32 v102, 1.0, v102
	v_add_f32_e32 v103, 1.0, v103
	v_add_f32_e32 v98, 1.0, v98
	v_add_f32_e32 v99, 1.0, v99
	v_rcp_f32_e32 v102, v102
	v_rcp_f32_e32 v103, v103
	v_add_f32_e32 v104, 1.0, v104
	v_add_f32_e32 v105, 1.0, v105
	v_rcp_f32_e32 v98, v98
	v_rcp_f32_e32 v99, v99
	v_add_f32_e32 v100, 1.0, v100
	v_add_f32_e32 v101, 1.0, v101
	v_rcp_f32_e32 v104, v104
	v_rcp_f32_e32 v105, v105
	v_rcp_f32_e32 v100, v100
	v_rcp_f32_e32 v101, v101
	v_lshl_or_b32 v111, v111, 8, v112
	v_or3_b32 v0, v111, v0, v110
	ds_write2_b32 v116, v0, v106 offset0:64 offset1:68
	v_mul_f32_e32 v0, 0x437f0000, v102
	v_mul_f32_e32 v102, 0x437f0000, v103
	v_mul_f32_e32 v98, 0x437f0000, v98
	v_mul_f32_e32 v99, 0x437f0000, v99
	v_rndne_f32_e32 v0, v0
	v_rndne_f32_e32 v102, v102
	v_mul_f32_e32 v103, 0x437f0000, v104
	v_mul_f32_e32 v104, 0x437f0000, v105
	v_rndne_f32_e32 v98, v98
	v_rndne_f32_e32 v99, v99
	v_mul_f32_e32 v100, 0x437f0000, v100
	v_mul_f32_e32 v101, 0x437f0000, v101
	v_max_f32_e32 v0, 1.0, v0
	v_max_f32_e32 v102, 1.0, v102
	v_rndne_f32_e32 v103, v103
	v_rndne_f32_e32 v104, v104
	v_max_f32_e32 v98, 1.0, v98
	v_max_f32_e32 v99, 1.0, v99
	v_rndne_f32_e32 v100, v100
	v_rndne_f32_e32 v101, v101
	v_cvt_u32_f32_e32 v0, v0
	v_cvt_u32_f32_e32 v102, v102
	v_max_f32_e32 v103, 1.0, v103
	v_max_f32_e32 v104, 1.0, v104
	v_cvt_u32_f32_e32 v98, v98
	v_cvt_u32_f32_e32 v99, v99
	v_max_f32_e32 v100, 1.0, v100
	v_max_f32_e32 v101, 1.0, v101
	v_cvt_u32_f32_sdwa v103, v103 dst_sel:WORD_1 dst_unused:UNUSED_PAD src0_sel:DWORD
	v_cvt_u32_f32_sdwa v104, v104 dst_sel:BYTE_3 dst_unused:UNUSED_PAD src0_sel:DWORD
	v_cvt_u32_f32_sdwa v100, v100 dst_sel:WORD_1 dst_unused:UNUSED_PAD src0_sel:DWORD
	v_cvt_u32_f32_sdwa v101, v101 dst_sel:BYTE_3 dst_unused:UNUSED_PAD src0_sel:DWORD
	v_lshl_or_b32 v0, v102, 8, v0
	v_lshl_or_b32 v98, v99, 8, v98
	v_or3_b32 v0, v0, v103, v104
	v_or3_b32 v98, v98, v100, v101
	ds_write2_b32 v116, v0, v98 offset0:72 offset1:76
	s_mov_b32 s72, s71
	s_mov_b32 s71, s75
	s_and_b64 vcc, exec, s[8:9]
	s_cbranch_vccz .LBB0_268
	s_branch .LBB0_269

; __device__ __forceinline__ float sigmoid_f(float v) { return __builtin_amdgcn_rcpf(1.f + __builtin_amdgcn_exp2f(-LOG2E * v)); }
; #define LAS __attribute__((address_space(3)))
; __device__ __forceinline__ void phase_gemm1(const Params& p, int layer, LAS unsigned char* lds) {
;     ...
;                         if (type == 4) {
;                             const float* bm = p.b_mg + layer * 3072 + (col0 - INW);
; #pragma unroll
;                             for (int m = 0; m < 4; m++) {
;                                 const float4 b4 = *(const float4*)(bm + m * 16 + fq * 4);
;                                 v[m][0] = sigmoid_f(v[m][0] + b4.x); v[m][1] = sigmoid_f(v[m][1] + b4.y);
;                                 v[m][2] = sigmoid_f(v[m][2] + b4.z); v[m][3] = sigmoid_f(v[m][3] + b4.w);
;                             }
;                         }
;                         if (type == 4) {
;                             LAS unsigned char* srow = lds + wid * 9216 + ((bj * 2 + n) * 16 + fr) * 80 + fq * 4;
; #pragma unroll
;                             for (int m = 0; m < 4; m++) {
;                                 const unsigned q0 = (unsigned)fmaxf(__builtin_rintf(v[m][0] * 255.f), 1.f), q1 = (unsigned)fmaxf(__builtin_rintf(v[m][1] * 255.f), 1.f);
;                                 const unsigned q2 = (unsigned)fmaxf(__builtin_rintf(v[m][2] * 255.f), 1.f), q3 = (unsigned)fmaxf(__builtin_rintf(v[m][3] * 255.f), 1.f);
;                                 *(LAS unsigned*)(srow + m * 16) = q0 | (q1 << 8) | (q2 << 16) | (q3 << 24);
;                             }
.LBB0_330:
	s_andn2_b64 vcc, exec, s[74:75]
	s_ashr_i32 s67, s66, 31
	v_readlane_b32 s74, v252, 16
	s_mov_b32 s69, s68
	s_cbranch_vccnz .LBB0_344
	s_lshl_b64 s[16:17], s[66:67], 2
	s_add_u32 s16, s74, s16
	s_addc_u32 s17, s69, s17
	v_mov_b32_e32 v131, v1
	v_lshl_add_u64 v[76:77], s[16:17], 0, v[130:131]
	s_movk_i32 s16, 0xb800
	s_mov_b32 s17, -1
	v_lshl_add_u64 v[68:69], v[76:77], 0, s[16:17]
	v_add_co_u32_e32 v76, vcc, 0xffffc000, v76
	s_nop 1
	v_addc_co_u32_e32 v77, vcc, -1, v77, vcc
	global_load_dwordx4 v[208:211], v[76:77], off offset:-2048
	global_load_dwordx4 v[212:215], v[68:69], off offset:64
	global_load_dwordx4 v[216:219], v[68:69], off offset:128
	global_load_dwordx4 v[220:223], v[68:69], off offset:192
	s_waitcnt vmcnt(3)
	v_add_f32_e32 v62, v62, v208
	v_mul_f32_e32 v62, 0xbfb8aa3b, v62
	v_exp_f32_e32 v62, v62
	s_nop 0
	v_add_f32_e32 v62, 1.0, v62
	v_rcp_f32_e32 v75, v62
	v_add_f32_e32 v62, v63, v209
	v_mul_f32_e32 v62, 0xbfb8aa3b, v62
	v_exp_f32_e32 v62, v62
	v_add_f32_e32 v63, v65, v211
	v_mul_f32_e32 v63, 0xbfb8aa3b, v63
	v_exp_f32_e32 v63, v63
	v_add_f32_e32 v62, 1.0, v62
	v_rcp_f32_e32 v67, v62
	v_add_f32_e32 v62, v64, v210
	v_mul_f32_e32 v62, 0xbfb8aa3b, v62
	v_exp_f32_e32 v62, v62
	v_add_f32_e32 v63, 1.0, v63
	v_rcp_f32_e32 v63, v63
	v_mul_f32_e32 v64, 0x437f0000, v75
	v_add_f32_e32 v62, 1.0, v62
	v_rcp_f32_e32 v62, v62
	v_mul_f32_e32 v65, 0x437f0000, v67
	v_rndne_f32_e32 v64, v64
	v_rndne_f32_e32 v65, v65
	v_mul_f32_e32 v62, 0x437f0000, v62
	v_mul_f32_e32 v63, 0x437f0000, v63
	v_max_f32_e32 v64, 1.0, v64
	v_max_f32_e32 v65, 1.0, v65
	v_rndne_f32_e32 v62, v62
	v_rndne_f32_e32 v63, v63
	v_cvt_u32_f32_e32 v64, v64
	v_cvt_u32_f32_e32 v65, v65
	v_max_f32_e32 v62, 1.0, v62
	v_max_f32_e32 v63, 1.0, v63
	v_cvt_u32_f32_sdwa v62, v62 dst_sel:WORD_1 dst_unused:UNUSED_PAD src0_sel:DWORD
	v_cvt_u32_f32_sdwa v63, v63 dst_sel:BYTE_3 dst_unused:UNUSED_PAD src0_sel:DWORD
	v_lshl_or_b32 v64, v65, 8, v64
	v_or3_b32 v62, v64, v62, v63
	s_waitcnt vmcnt(2)
	v_add_f32_e32 v58, v58, v212
	v_add_f32_e32 v59, v59, v213
	v_add_f32_e32 v60, v60, v214
	v_add_f32_e32 v61, v61, v215
	v_mul_f32_e32 v58, 0xbfb8aa3b, v58
	v_mul_f32_e32 v59, 0xbfb8aa3b, v59
	v_exp_f32_e32 v58, v58
	v_exp_f32_e32 v59, v59
	v_mul_f32_e32 v60, 0xbfb8aa3b, v60
	v_mul_f32_e32 v61, 0xbfb8aa3b, v61
	v_exp_f32_e32 v60, v60
	v_exp_f32_e32 v61, v61
	v_add_f32_e32 v58, 1.0, v58
	v_add_f32_e32 v59, 1.0, v59
	v_rcp_f32_e32 v58, v58
	v_rcp_f32_e32 v59, v59
	v_add_f32_e32 v60, 1.0, v60
	v_add_f32_e32 v61, 1.0, v61
	v_rcp_f32_e32 v60, v60
	v_rcp_f32_e32 v61, v61
	v_mul_f32_e32 v58, 0x437f0000, v58
	v_mul_f32_e32 v59, 0x437f0000, v59
	v_rndne_f32_e32 v58, v58
	v_rndne_f32_e32 v59, v59
	v_mul_f32_e32 v60, 0x437f0000, v60
	v_mul_f32_e32 v61, 0x437f0000, v61
	v_max_f32_e32 v58, 1.0, v58
	v_max_f32_e32 v59, 1.0, v59
	v_rndne_f32_e32 v60, v60
	v_rndne_f32_e32 v61, v61
	v_cvt_u32_f32_e32 v58, v58
	v_cvt_u32_f32_e32 v59, v59
	v_max_f32_e32 v60, 1.0, v60
	v_max_f32_e32 v61, 1.0, v61
	v_cvt_u32_f32_sdwa v60, v60 dst_sel:WORD_1 dst_unused:UNUSED_PAD src0_sel:DWORD
	v_cvt_u32_f32_sdwa v61, v61 dst_sel:BYTE_3 dst_unused:UNUSED_PAD src0_sel:DWORD
	v_lshl_or_b32 v58, v59, 8, v58
	v_or3_b32 v58, v58, v60, v61
	ds_write2_b32 v135, v62, v58 offset1:4
	s_waitcnt vmcnt(1)
	v_add_f32_e32 v54, v54, v216
	v_add_f32_e32 v55, v55, v217
	v_add_f32_e32 v56, v56, v218
	v_add_f32_e32 v57, v57, v219
	v_mul_f32_e32 v54, 0xbfb8aa3b, v54
	v_mul_f32_e32 v55, 0xbfb8aa3b, v55
	v_exp_f32_e32 v54, v54
	v_exp_f32_e32 v55, v55
	v_mul_f32_e32 v56, 0xbfb8aa3b, v56
	v_mul_f32_e32 v57, 0xbfb8aa3b, v57
	v_exp_f32_e32 v56, v56
	v_exp_f32_e32 v57, v57
	v_add_f32_e32 v54, 1.0, v54
	v_add_f32_e32 v55, 1.0, v55
	v_rcp_f32_e32 v54, v54
	v_rcp_f32_e32 v55, v55
	v_add_f32_e32 v56, 1.0, v56
	v_add_f32_e32 v57, 1.0, v57
	v_rcp_f32_e32 v56, v56
	v_rcp_f32_e32 v57, v57
	v_mul_f32_e32 v54, 0x437f0000, v54
	v_mul_f32_e32 v55, 0x437f0000, v55
	v_rndne_f32_e32 v54, v54
	v_rndne_f32_e32 v55, v55
	v_mul_f32_e32 v56, 0x437f0000, v56
	v_mul_f32_e32 v57, 0x437f0000, v57
	v_max_f32_e32 v54, 1.0, v54
	v_max_f32_e32 v55, 1.0, v55
	v_rndne_f32_e32 v56, v56
	v_rndne_f32_e32 v57, v57
	v_cvt_u32_f32_e32 v54, v54
	v_cvt_u32_f32_e32 v55, v55
	v_max_f32_e32 v56, 1.0, v56
	v_max_f32_e32 v57, 1.0, v57
	v_cvt_u32_f32_sdwa v56, v56 dst_sel:WORD_1 dst_unused:UNUSED_PAD src0_sel:DWORD
	v_cvt_u32_f32_sdwa v57, v57 dst_sel:BYTE_3 dst_unused:UNUSED_PAD src0_sel:DWORD
	v_lshl_or_b32 v54, v55, 8, v54
	v_or3_b32 v54, v54, v56, v57
	s_waitcnt vmcnt(0)
	v_add_f32_e32 v50, v50, v220
	v_add_f32_e32 v51, v51, v221
	v_mul_f32_e32 v50, 0xbfb8aa3b, v50
	v_mul_f32_e32 v51, 0xbfb8aa3b, v51
	v_add_f32_e32 v52, v52, v222
	v_add_f32_e32 v53, v53, v223
	v_exp_f32_e32 v50, v50
	v_exp_f32_e32 v51, v51
	v_mul_f32_e32 v52, 0xbfb8aa3b, v52
	v_mul_f32_e32 v53, 0xbfb8aa3b, v53
	v_exp_f32_e32 v52, v52
	v_exp_f32_e32 v53, v53
	v_add_f32_e32 v50, 1.0, v50
	v_add_f32_e32 v51, 1.0, v51
	v_rcp_f32_e32 v50, v50
	v_rcp_f32_e32 v51, v51
	v_add_f32_e32 v52, 1.0, v52
	v_add_f32_e32 v53, 1.0, v53
	v_rcp_f32_e32 v52, v52
	v_rcp_f32_e32 v53, v53
	v_mul_f32_e32 v50, 0x437f0000, v50
	v_mul_f32_e32 v51, 0x437f0000, v51
	v_rndne_f32_e32 v50, v50
	v_rndne_f32_e32 v51, v51
	v_mul_f32_e32 v52, 0x437f0000, v52
	v_mul_f32_e32 v53, 0x437f0000, v53
	v_max_f32_e32 v50, 1.0, v50
	v_max_f32_e32 v51, 1.0, v51
	v_rndne_f32_e32 v52, v52
	v_rndne_f32_e32 v53, v53
	v_cvt_u32_f32_e32 v50, v50
	v_cvt_u32_f32_e32 v51, v51
	v_max_f32_e32 v52, 1.0, v52
	v_max_f32_e32 v53, 1.0, v53
	v_cvt_u32_f32_sdwa v52, v52 dst_sel:WORD_1 dst_unused:UNUSED_PAD src0_sel:DWORD
	v_cvt_u32_f32_sdwa v53, v53 dst_sel:BYTE_3 dst_unused:UNUSED_PAD src0_sel:DWORD
	v_lshl_or_b32 v50, v51, 8, v50
	v_or3_b32 v50, v50, v52, v53
	ds_write2_b32 v135, v54, v50 offset0:8 offset1:12
	s_and_b64 vcc, exec, s[10:11]
	s_mov_b32 s75, s71
	s_cbranch_vccz .LBB0_345

; __device__ __forceinline__ float sigmoid_f(float v) { return __builtin_amdgcn_rcpf(1.f + __builtin_amdgcn_exp2f(-LOG2E * v)); }
; #define LAS __attribute__((address_space(3)))
; __device__ __forceinline__ void phase_gemm1(const Params& p, int layer, LAS unsigned char* lds) {
;     ...
;                         if (type == 4) {
;                             const float* bm = p.b_mg + layer * 3072 + (col0 - INW);
; #pragma unroll
;                             for (int m = 0; m < 4; m++) {
;                                 const float4 b4 = *(const float4*)(bm + m * 16 + fq * 4);
;                                 v[m][0] = sigmoid_f(v[m][0] + b4.x); v[m][1] = sigmoid_f(v[m][1] + b4.y);
;                                 v[m][2] = sigmoid_f(v[m][2] + b4.z); v[m][3] = sigmoid_f(v[m][3] + b4.w);
;                             }
;                         }
;                         if (type == 4) {
;                             LAS unsigned char* srow = lds + wid * 9216 + ((bj * 2 + n) * 16 + fr) * 80 + fq * 4;
; #pragma unroll
;                             for (int m = 0; m < 4; m++) {
;                                 const unsigned q0 = (unsigned)fmaxf(__builtin_rintf(v[m][0] * 255.f), 1.f), q1 = (unsigned)fmaxf(__builtin_rintf(v[m][1] * 255.f), 1.f);
;                                 const unsigned q2 = (unsigned)fmaxf(__builtin_rintf(v[m][2] * 255.f), 1.f), q3 = (unsigned)fmaxf(__builtin_rintf(v[m][3] * 255.f), 1.f);
;                                 *(LAS unsigned*)(srow + m * 16) = q0 | (q1 << 8) | (q2 << 16) | (q3 << 24);
;                             }
.LBB0_337:
	s_lshl_b64 s[4:5], s[66:67], 2
	s_add_u32 s4, s74, s4
	s_addc_u32 s5, s69, s5
	v_mov_b32_e32 v131, v1
	v_lshl_add_u64 v[52:53], s[4:5], 0, v[130:131]
	s_movk_i32 s4, 0xb800
	s_mov_b32 s5, -1
	v_lshl_add_u64 v[50:51], v[52:53], 0, s[4:5]
	v_add_co_u32_e32 v52, vcc, 0xffffc000, v52
	s_nop 1
	v_addc_co_u32_e32 v53, vcc, -1, v53, vcc
	v_add_f32_e32 v46, v46, v208
	v_mul_f32_e32 v46, 0xbfb8aa3b, v46
	v_exp_f32_e32 v46, v46
	s_nop 0
	v_add_f32_e32 v46, 1.0, v46
	v_rcp_f32_e32 v53, v46
	v_add_f32_e32 v46, v47, v209
	v_mul_f32_e32 v46, 0xbfb8aa3b, v46
	v_exp_f32_e32 v46, v46
	v_add_f32_e32 v47, v49, v211
	v_mul_f32_e32 v47, 0xbfb8aa3b, v47
	v_exp_f32_e32 v47, v47
	v_add_f32_e32 v46, 1.0, v46
	v_rcp_f32_e32 v52, v46
	v_add_f32_e32 v46, v48, v210
	v_mul_f32_e32 v46, 0xbfb8aa3b, v46
	v_exp_f32_e32 v46, v46
	v_add_f32_e32 v47, 1.0, v47
	v_rcp_f32_e32 v47, v47
	v_add_f32_e32 v46, 1.0, v46
	v_rcp_f32_e32 v46, v46
	v_mul_f32_e32 v47, 0x437f0000, v47
	v_rndne_f32_e32 v47, v47
	v_max_f32_e32 v47, 1.0, v47
	v_mul_f32_e32 v46, 0x437f0000, v46
	v_rndne_f32_e32 v46, v46
	v_max_f32_e32 v46, 1.0, v46
	v_cvt_u32_f32_sdwa v46, v46 dst_sel:WORD_1 dst_unused:UNUSED_PAD src0_sel:DWORD
	v_cvt_u32_f32_sdwa v47, v47 dst_sel:BYTE_3 dst_unused:UNUSED_PAD src0_sel:DWORD
	v_add_f32_e32 v42, v42, v212
	v_add_f32_e32 v43, v43, v213
	v_add_f32_e32 v44, v44, v214
	v_add_f32_e32 v45, v45, v215
	v_mul_f32_e32 v42, 0xbfb8aa3b, v42
	v_mul_f32_e32 v43, 0xbfb8aa3b, v43
	v_exp_f32_e32 v42, v42
	v_exp_f32_e32 v43, v43
	v_mul_f32_e32 v44, 0xbfb8aa3b, v44
	v_mul_f32_e32 v45, 0xbfb8aa3b, v45
	v_exp_f32_e32 v44, v44
	v_exp_f32_e32 v45, v45
	v_add_f32_e32 v42, 1.0, v42
	v_add_f32_e32 v43, 1.0, v43
	v_rcp_f32_e32 v42, v42
	v_rcp_f32_e32 v43, v43
	v_add_f32_e32 v44, 1.0, v44
	v_add_f32_e32 v45, 1.0, v45
	v_rcp_f32_e32 v44, v44
	v_rcp_f32_e32 v45, v45
	v_mul_f32_e32 v42, 0x437f0000, v42
	v_mul_f32_e32 v43, 0x437f0000, v43
	v_rndne_f32_e32 v42, v42
	v_rndne_f32_e32 v43, v43
	v_mul_f32_e32 v44, 0x437f0000, v44
	v_mul_f32_e32 v45, 0x437f0000, v45
	v_max_f32_e32 v42, 1.0, v42
	v_max_f32_e32 v43, 1.0, v43
	v_rndne_f32_e32 v44, v44
	v_rndne_f32_e32 v45, v45
	v_cvt_u32_f32_e32 v42, v42
	v_cvt_u32_f32_e32 v43, v43
	v_max_f32_e32 v44, 1.0, v44
	v_max_f32_e32 v45, 1.0, v45
	v_cvt_u32_f32_sdwa v44, v44 dst_sel:WORD_1 dst_unused:UNUSED_PAD src0_sel:DWORD
	v_cvt_u32_f32_sdwa v45, v45 dst_sel:BYTE_3 dst_unused:UNUSED_PAD src0_sel:DWORD
	v_lshl_or_b32 v42, v43, 8, v42
	v_or3_b32 v42, v42, v44, v45
	v_add_f32_e32 v38, v38, v216
	v_add_f32_e32 v39, v39, v217
	v_add_f32_e32 v34, v34, v220
	v_add_f32_e32 v35, v35, v221
	v_mul_f32_e32 v38, 0xbfb8aa3b, v38
	v_mul_f32_e32 v39, 0xbfb8aa3b, v39
	v_add_f32_e32 v40, v40, v218
	v_add_f32_e32 v41, v41, v219
	v_mul_f32_e32 v34, 0xbfb8aa3b, v34
	v_mul_f32_e32 v35, 0xbfb8aa3b, v35
	v_add_f32_e32 v36, v36, v222
	v_add_f32_e32 v37, v37, v223
	v_exp_f32_e32 v38, v38
	v_exp_f32_e32 v39, v39
	v_mul_f32_e32 v40, 0xbfb8aa3b, v40
	v_mul_f32_e32 v41, 0xbfb8aa3b, v41
	v_exp_f32_e32 v34, v34
	v_exp_f32_e32 v35, v35
	v_mul_f32_e32 v36, 0xbfb8aa3b, v36
	v_mul_f32_e32 v37, 0xbfb8aa3b, v37
	v_exp_f32_e32 v40, v40
	v_exp_f32_e32 v41, v41
	v_exp_f32_e32 v36, v36
	v_exp_f32_e32 v37, v37
	v_add_f32_e32 v38, 1.0, v38
	v_add_f32_e32 v39, 1.0, v39
	v_add_f32_e32 v34, 1.0, v34
	v_add_f32_e32 v35, 1.0, v35
	v_rcp_f32_e32 v38, v38
	v_rcp_f32_e32 v39, v39
	v_add_f32_e32 v40, 1.0, v40
	v_add_f32_e32 v41, 1.0, v41
	v_rcp_f32_e32 v34, v34
	v_rcp_f32_e32 v35, v35
	v_add_f32_e32 v36, 1.0, v36
	v_add_f32_e32 v37, 1.0, v37
	v_rcp_f32_e32 v40, v40
	v_rcp_f32_e32 v41, v41
	v_rcp_f32_e32 v36, v36
	v_rcp_f32_e32 v37, v37
	v_mul_f32_e32 v48, 0x437f0000, v53
	v_mul_f32_e32 v49, 0x437f0000, v52
	v_mul_f32_e32 v38, 0x437f0000, v38
	v_mul_f32_e32 v39, 0x437f0000, v39
	v_mul_f32_e32 v34, 0x437f0000, v34
	v_mul_f32_e32 v35, 0x437f0000, v35
	v_rndne_f32_e32 v48, v48
	v_rndne_f32_e32 v49, v49
	v_rndne_f32_e32 v38, v38
	v_rndne_f32_e32 v39, v39
	v_mul_f32_e32 v40, 0x437f0000, v40
	v_mul_f32_e32 v41, 0x437f0000, v41
	v_rndne_f32_e32 v34, v34
	v_rndne_f32_e32 v35, v35
	v_mul_f32_e32 v36, 0x437f0000, v36
	v_mul_f32_e32 v37, 0x437f0000, v37
	v_max_f32_e32 v48, 1.0, v48
	v_max_f32_e32 v49, 1.0, v49
	v_max_f32_e32 v38, 1.0, v38
	v_max_f32_e32 v39, 1.0, v39
	v_rndne_f32_e32 v40, v40
	v_rndne_f32_e32 v41, v41
	v_max_f32_e32 v34, 1.0, v34
	v_max_f32_e32 v35, 1.0, v35
	v_rndne_f32_e32 v36, v36
	v_rndne_f32_e32 v37, v37
	v_cvt_u32_f32_e32 v48, v48
	v_cvt_u32_f32_e32 v49, v49
	v_cvt_u32_f32_e32 v38, v38
	v_cvt_u32_f32_e32 v39, v39
	v_max_f32_e32 v40, 1.0, v40
	v_max_f32_e32 v41, 1.0, v41
	v_cvt_u32_f32_e32 v34, v34
	v_cvt_u32_f32_e32 v35, v35
	v_max_f32_e32 v36, 1.0, v36
	v_max_f32_e32 v37, 1.0, v37
	v_cvt_u32_f32_sdwa v40, v40 dst_sel:WORD_1 dst_unused:UNUSED_PAD src0_sel:DWORD
	v_cvt_u32_f32_sdwa v41, v41 dst_sel:BYTE_3 dst_unused:UNUSED_PAD src0_sel:DWORD
	v_cvt_u32_f32_sdwa v36, v36 dst_sel:WORD_1 dst_unused:UNUSED_PAD src0_sel:DWORD
	v_cvt_u32_f32_sdwa v37, v37 dst_sel:BYTE_3 dst_unused:UNUSED_PAD src0_sel:DWORD
	v_lshl_or_b32 v48, v49, 8, v48
	v_lshl_or_b32 v38, v39, 8, v38
	v_lshl_or_b32 v34, v35, 8, v34
	v_or3_b32 v46, v48, v46, v47
	v_or3_b32 v38, v38, v40, v41
	v_or3_b32 v34, v34, v36, v37
	ds_write2_b32 v116, v46, v42 offset0:64 offset1:68
	ds_write2_b32 v116, v38, v34 offset0:72 offset1:76
	s_and_b64 vcc, exec, s[10:11]
	s_cbranch_vccz .LBB0_351

; __device__ __forceinline__ float sigmoid_f(float v) { return __builtin_amdgcn_rcpf(1.f + __builtin_amdgcn_exp2f(-LOG2E * v)); }
; #define LAS __attribute__((address_space(3)))
; __device__ __forceinline__ void phase_gemm1(const Params& p, int layer, LAS unsigned char* lds) {
;     ...
;                         if (type == 4) {
;                             const float* bm = p.b_mg + layer * 3072 + (col0 - INW);
; #pragma unroll
;                             for (int m = 0; m < 4; m++) {
;                                 const float4 b4 = *(const float4*)(bm + m * 16 + fq * 4);
;                                 v[m][0] = sigmoid_f(v[m][0] + b4.x); v[m][1] = sigmoid_f(v[m][1] + b4.y);
;                                 v[m][2] = sigmoid_f(v[m][2] + b4.z); v[m][3] = sigmoid_f(v[m][3] + b4.w);
;                             }
;                         }
;                         if (type == 4) {
;                             LAS unsigned char* srow = lds + wid * 9216 + ((bj * 2 + n) * 16 + fr) * 80 + fq * 4;
; #pragma unroll
;                             for (int m = 0; m < 4; m++) {
;                                 const unsigned q0 = (unsigned)fmaxf(__builtin_rintf(v[m][0] * 255.f), 1.f), q1 = (unsigned)fmaxf(__builtin_rintf(v[m][1] * 255.f), 1.f);
;                                 const unsigned q2 = (unsigned)fmaxf(__builtin_rintf(v[m][2] * 255.f), 1.f), q3 = (unsigned)fmaxf(__builtin_rintf(v[m][3] * 255.f), 1.f);
;                                 *(LAS unsigned*)(srow + m * 16) = q0 | (q1 << 8) | (q2 << 16) | (q3 << 24);
;                             }
.LBB0_343:
	s_lshl_b64 s[4:5], s[66:67], 2
	s_add_u32 s4, s74, s4
	s_addc_u32 s5, s69, s5
	v_mov_b32_e32 v131, v1
	v_lshl_add_u64 v[36:37], s[4:5], 0, v[130:131]
	s_movk_i32 s4, 0xb800
	s_mov_b32 s5, -1
	v_lshl_add_u64 v[34:35], v[36:37], 0, s[4:5]
	v_add_co_u32_e32 v36, vcc, 0xffffc000, v36
	s_nop 1
	v_addc_co_u32_e32 v37, vcc, -1, v37, vcc
	v_add_f32_e32 v30, v30, v208
	v_mul_f32_e32 v30, 0xbfb8aa3b, v30
	v_exp_f32_e32 v30, v30
	s_nop 0
	v_add_f32_e32 v30, 1.0, v30
	v_rcp_f32_e32 v37, v30
	v_add_f32_e32 v30, v31, v209
	v_mul_f32_e32 v30, 0xbfb8aa3b, v30
	v_exp_f32_e32 v30, v30
	v_add_f32_e32 v31, v33, v211
	v_mul_f32_e32 v31, 0xbfb8aa3b, v31
	v_exp_f32_e32 v31, v31
	v_add_f32_e32 v30, 1.0, v30
	v_rcp_f32_e32 v36, v30
	v_add_f32_e32 v30, v32, v210
	v_mul_f32_e32 v30, 0xbfb8aa3b, v30
	v_exp_f32_e32 v30, v30
	v_add_f32_e32 v31, 1.0, v31
	v_rcp_f32_e32 v31, v31
	v_add_f32_e32 v30, 1.0, v30
	v_rcp_f32_e32 v30, v30
	v_mul_f32_e32 v31, 0x437f0000, v31
	v_rndne_f32_e32 v31, v31
	v_max_f32_e32 v31, 1.0, v31
	v_mul_f32_e32 v30, 0x437f0000, v30
	v_rndne_f32_e32 v30, v30
	v_max_f32_e32 v30, 1.0, v30
	v_cvt_u32_f32_sdwa v30, v30 dst_sel:WORD_1 dst_unused:UNUSED_PAD src0_sel:DWORD
	v_cvt_u32_f32_sdwa v31, v31 dst_sel:BYTE_3 dst_unused:UNUSED_PAD src0_sel:DWORD
	v_add_f32_e32 v26, v26, v212
	v_add_f32_e32 v27, v27, v213
	v_add_f32_e32 v28, v28, v214
	v_add_f32_e32 v29, v29, v215
	v_mul_f32_e32 v26, 0xbfb8aa3b, v26
	v_mul_f32_e32 v27, 0xbfb8aa3b, v27
	v_exp_f32_e32 v26, v26
	v_exp_f32_e32 v27, v27
	v_mul_f32_e32 v28, 0xbfb8aa3b, v28
	v_mul_f32_e32 v29, 0xbfb8aa3b, v29
	v_exp_f32_e32 v28, v28
	v_exp_f32_e32 v29, v29
	v_add_f32_e32 v26, 1.0, v26
	v_add_f32_e32 v27, 1.0, v27
	v_rcp_f32_e32 v26, v26
	v_rcp_f32_e32 v27, v27
	v_add_f32_e32 v28, 1.0, v28
	v_add_f32_e32 v29, 1.0, v29
	v_rcp_f32_e32 v28, v28
	v_rcp_f32_e32 v29, v29
	v_mul_f32_e32 v26, 0x437f0000, v26
	v_mul_f32_e32 v27, 0x437f0000, v27
	v_rndne_f32_e32 v26, v26
	v_rndne_f32_e32 v27, v27
	v_mul_f32_e32 v28, 0x437f0000, v28
	v_mul_f32_e32 v29, 0x437f0000, v29
	v_max_f32_e32 v26, 1.0, v26
	v_max_f32_e32 v27, 1.0, v27
	v_rndne_f32_e32 v28, v28
	v_rndne_f32_e32 v29, v29
	v_cvt_u32_f32_e32 v26, v26
	v_cvt_u32_f32_e32 v27, v27
	v_max_f32_e32 v28, 1.0, v28
	v_max_f32_e32 v29, 1.0, v29
	v_cvt_u32_f32_sdwa v28, v28 dst_sel:WORD_1 dst_unused:UNUSED_PAD src0_sel:DWORD
	v_cvt_u32_f32_sdwa v29, v29 dst_sel:BYTE_3 dst_unused:UNUSED_PAD src0_sel:DWORD
	v_lshl_or_b32 v26, v27, 8, v26
	v_or3_b32 v26, v26, v28, v29
	v_add_f32_e32 v22, v22, v216
	v_add_f32_e32 v23, v23, v217
	v_add_f32_e32 v18, v18, v220
	v_add_f32_e32 v19, v19, v221
	v_mul_f32_e32 v22, 0xbfb8aa3b, v22
	v_mul_f32_e32 v23, 0xbfb8aa3b, v23
	v_add_f32_e32 v24, v24, v218
	v_add_f32_e32 v25, v25, v219
	v_mul_f32_e32 v18, 0xbfb8aa3b, v18
	v_mul_f32_e32 v19, 0xbfb8aa3b, v19
	v_add_f32_e32 v20, v20, v222
	v_add_f32_e32 v21, v21, v223
	v_exp_f32_e32 v22, v22
	v_exp_f32_e32 v23, v23
	v_mul_f32_e32 v24, 0xbfb8aa3b, v24
	v_mul_f32_e32 v25, 0xbfb8aa3b, v25
	v_exp_f32_e32 v18, v18
	v_exp_f32_e32 v19, v19
	v_mul_f32_e32 v20, 0xbfb8aa3b, v20
	v_mul_f32_e32 v21, 0xbfb8aa3b, v21
	v_exp_f32_e32 v24, v24
	v_exp_f32_e32 v25, v25
	v_exp_f32_e32 v20, v20
	v_exp_f32_e32 v21, v21
	v_add_f32_e32 v22, 1.0, v22
	v_add_f32_e32 v23, 1.0, v23
	v_add_f32_e32 v18, 1.0, v18
	v_add_f32_e32 v19, 1.0, v19
	v_rcp_f32_e32 v22, v22
	v_rcp_f32_e32 v23, v23
	v_add_f32_e32 v24, 1.0, v24
	v_add_f32_e32 v25, 1.0, v25
	v_rcp_f32_e32 v18, v18
	v_rcp_f32_e32 v19, v19
	v_add_f32_e32 v20, 1.0, v20
	v_add_f32_e32 v21, 1.0, v21
	v_rcp_f32_e32 v24, v24
	v_rcp_f32_e32 v25, v25
	v_rcp_f32_e32 v20, v20
	v_rcp_f32_e32 v21, v21
	v_mul_f32_e32 v32, 0x437f0000, v37
	v_mul_f32_e32 v33, 0x437f0000, v36
	v_mul_f32_e32 v22, 0x437f0000, v22
	v_mul_f32_e32 v23, 0x437f0000, v23
	v_mul_f32_e32 v18, 0x437f0000, v18
	v_mul_f32_e32 v19, 0x437f0000, v19
	v_rndne_f32_e32 v32, v32
	v_rndne_f32_e32 v33, v33
	v_rndne_f32_e32 v22, v22
	v_rndne_f32_e32 v23, v23
	v_mul_f32_e32 v24, 0x437f0000, v24
	v_mul_f32_e32 v25, 0x437f0000, v25
	v_rndne_f32_e32 v18, v18
	v_rndne_f32_e32 v19, v19
	v_mul_f32_e32 v20, 0x437f0000, v20
	v_mul_f32_e32 v21, 0x437f0000, v21
	v_max_f32_e32 v32, 1.0, v32
	v_max_f32_e32 v33, 1.0, v33
	v_max_f32_e32 v22, 1.0, v22
	v_max_f32_e32 v23, 1.0, v23
	v_rndne_f32_e32 v24, v24
	v_rndne_f32_e32 v25, v25
	v_max_f32_e32 v18, 1.0, v18
	v_max_f32_e32 v19, 1.0, v19
	v_rndne_f32_e32 v20, v20
	v_rndne_f32_e32 v21, v21
	v_cvt_u32_f32_e32 v32, v32
	v_cvt_u32_f32_e32 v33, v33
	v_cvt_u32_f32_e32 v22, v22
	v_cvt_u32_f32_e32 v23, v23
	v_max_f32_e32 v24, 1.0, v24
	v_max_f32_e32 v25, 1.0, v25
	v_cvt_u32_f32_e32 v18, v18
	v_cvt_u32_f32_e32 v19, v19
	v_max_f32_e32 v20, 1.0, v20
	v_max_f32_e32 v21, 1.0, v21
	v_cvt_u32_f32_sdwa v24, v24 dst_sel:WORD_1 dst_unused:UNUSED_PAD src0_sel:DWORD
	v_cvt_u32_f32_sdwa v25, v25 dst_sel:BYTE_3 dst_unused:UNUSED_PAD src0_sel:DWORD
	v_cvt_u32_f32_sdwa v20, v20 dst_sel:WORD_1 dst_unused:UNUSED_PAD src0_sel:DWORD
	v_cvt_u32_f32_sdwa v21, v21 dst_sel:BYTE_3 dst_unused:UNUSED_PAD src0_sel:DWORD
	v_lshl_or_b32 v32, v33, 8, v32
	v_lshl_or_b32 v22, v23, 8, v22
	v_lshl_or_b32 v18, v19, 8, v18
	v_or3_b32 v30, v32, v30, v31
	v_or3_b32 v22, v22, v24, v25
	v_or3_b32 v18, v18, v20, v21
	ds_write2_b32 v100, v30, v26 offset1:4
	ds_write2_b32 v100, v22, v18 offset0:8 offset1:12
	s_mov_b32 s16, 0x7fffffe0
	s_and_b64 vcc, exec, s[10:11]
	s_cbranch_vccz .LBB0_357
	s_branch .LBB0_358

; __device__ __forceinline__ float sigmoid_f(float v) { return __builtin_amdgcn_rcpf(1.f + __builtin_amdgcn_exp2f(-LOG2E * v)); }
; #define LAS __attribute__((address_space(3)))
; __device__ __forceinline__ void phase_gemm1(const Params& p, int layer, LAS unsigned char* lds) {
;     ...
;                         if (type == 4) {
;                             const float* bm = p.b_mg + layer * 3072 + (col0 - INW);
; #pragma unroll
;                             for (int m = 0; m < 4; m++) {
;                                 const float4 b4 = *(const float4*)(bm + m * 16 + fq * 4);
;                                 v[m][0] = sigmoid_f(v[m][0] + b4.x); v[m][1] = sigmoid_f(v[m][1] + b4.y);
;                                 v[m][2] = sigmoid_f(v[m][2] + b4.z); v[m][3] = sigmoid_f(v[m][3] + b4.w);
;                             }
;                         }
;                         if (type == 4) {
;                             LAS unsigned char* srow = lds + wid * 9216 + ((bj * 2 + n) * 16 + fr) * 80 + fq * 4;
; #pragma unroll
;                             for (int m = 0; m < 4; m++) {
;                                 const unsigned q0 = (unsigned)fmaxf(__builtin_rintf(v[m][0] * 255.f), 1.f), q1 = (unsigned)fmaxf(__builtin_rintf(v[m][1] * 255.f), 1.f);
;                                 const unsigned q2 = (unsigned)fmaxf(__builtin_rintf(v[m][2] * 255.f), 1.f), q3 = (unsigned)fmaxf(__builtin_rintf(v[m][3] * 255.f), 1.f);
;                                 *(LAS unsigned*)(srow + m * 16) = q0 | (q1 << 8) | (q2 << 16) | (q3 << 24);
;                             }
.LBB0_367:
	s_lshl_b64 s[4:5], s[66:67], 2
	s_add_u32 s4, s74, s4
	s_addc_u32 s5, s69, s5
	v_mov_b32_e32 v131, v1
	v_lshl_add_u64 v[20:21], s[4:5], 0, v[130:131]
	s_movk_i32 s4, 0xb800
	s_mov_b32 s5, -1
	v_lshl_add_u64 v[18:19], v[20:21], 0, s[4:5]
	v_add_co_u32_e32 v20, vcc, 0xffffc000, v20
	s_nop 1
	v_addc_co_u32_e32 v21, vcc, -1, v21, vcc
	v_add_f32_e32 v14, v14, v208
	v_mul_f32_e32 v14, 0xbfb8aa3b, v14
	v_exp_f32_e32 v14, v14
	s_nop 0
	v_add_f32_e32 v14, 1.0, v14
	v_rcp_f32_e32 v21, v14
	v_add_f32_e32 v14, v15, v209
	v_mul_f32_e32 v14, 0xbfb8aa3b, v14
	v_exp_f32_e32 v14, v14
	v_add_f32_e32 v15, v17, v211
	v_mul_f32_e32 v15, 0xbfb8aa3b, v15
	v_exp_f32_e32 v15, v15
	v_add_f32_e32 v14, 1.0, v14
	v_rcp_f32_e32 v20, v14
	v_add_f32_e32 v14, v16, v210
	v_mul_f32_e32 v14, 0xbfb8aa3b, v14
	v_exp_f32_e32 v14, v14
	v_add_f32_e32 v15, 1.0, v15
	v_rcp_f32_e32 v15, v15
	v_add_f32_e32 v14, 1.0, v14
	v_rcp_f32_e32 v14, v14
	v_mul_f32_e32 v15, 0x437f0000, v15
	v_rndne_f32_e32 v15, v15
	v_max_f32_e32 v15, 1.0, v15
	v_mul_f32_e32 v14, 0x437f0000, v14
	v_rndne_f32_e32 v14, v14
	v_max_f32_e32 v14, 1.0, v14
	v_cvt_u32_f32_sdwa v14, v14 dst_sel:WORD_1 dst_unused:UNUSED_PAD src0_sel:DWORD
	v_cvt_u32_f32_sdwa v15, v15 dst_sel:BYTE_3 dst_unused:UNUSED_PAD src0_sel:DWORD
	v_add_f32_e32 v10, v10, v212
	v_add_f32_e32 v11, v11, v213
	v_add_f32_e32 v12, v12, v214
	v_add_f32_e32 v13, v13, v215
	v_mul_f32_e32 v10, 0xbfb8aa3b, v10
	v_mul_f32_e32 v11, 0xbfb8aa3b, v11
	v_exp_f32_e32 v10, v10
	v_exp_f32_e32 v11, v11
	v_mul_f32_e32 v12, 0xbfb8aa3b, v12
	v_mul_f32_e32 v13, 0xbfb8aa3b, v13
	v_exp_f32_e32 v12, v12
	v_exp_f32_e32 v13, v13
	v_add_f32_e32 v10, 1.0, v10
	v_add_f32_e32 v11, 1.0, v11
	v_rcp_f32_e32 v10, v10
	v_rcp_f32_e32 v11, v11
	v_add_f32_e32 v12, 1.0, v12
	v_add_f32_e32 v13, 1.0, v13
	v_rcp_f32_e32 v12, v12
	v_rcp_f32_e32 v13, v13
	v_mul_f32_e32 v10, 0x437f0000, v10
	v_mul_f32_e32 v11, 0x437f0000, v11
	v_rndne_f32_e32 v10, v10
	v_rndne_f32_e32 v11, v11
	v_mul_f32_e32 v12, 0x437f0000, v12
	v_mul_f32_e32 v13, 0x437f0000, v13
	v_max_f32_e32 v10, 1.0, v10
	v_max_f32_e32 v11, 1.0, v11
	v_rndne_f32_e32 v12, v12
	v_rndne_f32_e32 v13, v13
	v_cvt_u32_f32_e32 v10, v10
	v_cvt_u32_f32_e32 v11, v11
	v_max_f32_e32 v12, 1.0, v12
	v_max_f32_e32 v13, 1.0, v13
	v_cvt_u32_f32_sdwa v12, v12 dst_sel:WORD_1 dst_unused:UNUSED_PAD src0_sel:DWORD
	v_cvt_u32_f32_sdwa v13, v13 dst_sel:BYTE_3 dst_unused:UNUSED_PAD src0_sel:DWORD
	v_lshl_or_b32 v10, v11, 8, v10
	v_or3_b32 v10, v10, v12, v13
	v_add_f32_e32 v6, v6, v216
	v_add_f32_e32 v7, v7, v217
	v_add_f32_e32 v2, v2, v220
	v_add_f32_e32 v3, v3, v221
	v_mul_f32_e32 v6, 0xbfb8aa3b, v6
	v_mul_f32_e32 v7, 0xbfb8aa3b, v7
	v_add_f32_e32 v8, v8, v218
	v_add_f32_e32 v9, v9, v219
	v_mul_f32_e32 v2, 0xbfb8aa3b, v2
	v_mul_f32_e32 v3, 0xbfb8aa3b, v3
	v_add_f32_e32 v4, v4, v222
	v_add_f32_e32 v5, v5, v223
	v_exp_f32_e32 v6, v6
	v_exp_f32_e32 v7, v7
	v_mul_f32_e32 v8, 0xbfb8aa3b, v8
	v_mul_f32_e32 v9, 0xbfb8aa3b, v9
	v_exp_f32_e32 v2, v2
	v_exp_f32_e32 v3, v3
	v_mul_f32_e32 v4, 0xbfb8aa3b, v4
	v_mul_f32_e32 v5, 0xbfb8aa3b, v5
	v_exp_f32_e32 v8, v8
	v_exp_f32_e32 v9, v9
	v_exp_f32_e32 v4, v4
	v_exp_f32_e32 v5, v5
	v_add_f32_e32 v6, 1.0, v6
	v_add_f32_e32 v7, 1.0, v7
	v_add_f32_e32 v2, 1.0, v2
	v_add_f32_e32 v3, 1.0, v3
	v_rcp_f32_e32 v6, v6
	v_rcp_f32_e32 v7, v7
	v_add_f32_e32 v8, 1.0, v8
	v_add_f32_e32 v9, 1.0, v9
	v_rcp_f32_e32 v2, v2
	v_rcp_f32_e32 v3, v3
	v_add_f32_e32 v4, 1.0, v4
	v_add_f32_e32 v5, 1.0, v5
	v_rcp_f32_e32 v8, v8
	v_rcp_f32_e32 v9, v9
	v_rcp_f32_e32 v4, v4
	v_rcp_f32_e32 v5, v5
	v_mul_f32_e32 v16, 0x437f0000, v21
	v_mul_f32_e32 v17, 0x437f0000, v20
	v_mul_f32_e32 v6, 0x437f0000, v6
	v_mul_f32_e32 v7, 0x437f0000, v7
	v_mul_f32_e32 v2, 0x437f0000, v2
	v_mul_f32_e32 v3, 0x437f0000, v3
	v_rndne_f32_e32 v16, v16
	v_rndne_f32_e32 v17, v17
	v_rndne_f32_e32 v6, v6
	v_rndne_f32_e32 v7, v7
	v_mul_f32_e32 v8, 0x437f0000, v8
	v_mul_f32_e32 v9, 0x437f0000, v9
	v_rndne_f32_e32 v2, v2
	v_rndne_f32_e32 v3, v3
	v_mul_f32_e32 v4, 0x437f0000, v4
	v_mul_f32_e32 v5, 0x437f0000, v5
	v_max_f32_e32 v16, 1.0, v16
	v_max_f32_e32 v17, 1.0, v17
	v_max_f32_e32 v6, 1.0, v6
	v_max_f32_e32 v7, 1.0, v7
	v_rndne_f32_e32 v8, v8
	v_rndne_f32_e32 v9, v9
	v_max_f32_e32 v2, 1.0, v2
	v_max_f32_e32 v3, 1.0, v3
	v_rndne_f32_e32 v4, v4
	v_rndne_f32_e32 v5, v5
	v_cvt_u32_f32_e32 v16, v16
	v_cvt_u32_f32_e32 v17, v17
	v_cvt_u32_f32_e32 v6, v6
	v_cvt_u32_f32_e32 v7, v7
	v_max_f32_e32 v8, 1.0, v8
	v_max_f32_e32 v9, 1.0, v9
	v_cvt_u32_f32_e32 v2, v2
	v_cvt_u32_f32_e32 v3, v3
	v_max_f32_e32 v4, 1.0, v4
	v_max_f32_e32 v5, 1.0, v5
	v_cvt_u32_f32_sdwa v8, v8 dst_sel:WORD_1 dst_unused:UNUSED_PAD src0_sel:DWORD
	v_cvt_u32_f32_sdwa v9, v9 dst_sel:BYTE_3 dst_unused:UNUSED_PAD src0_sel:DWORD
	v_cvt_u32_f32_sdwa v4, v4 dst_sel:WORD_1 dst_unused:UNUSED_PAD src0_sel:DWORD
	v_cvt_u32_f32_sdwa v5, v5 dst_sel:BYTE_3 dst_unused:UNUSED_PAD src0_sel:DWORD
	v_lshl_or_b32 v16, v17, 8, v16
	v_lshl_or_b32 v6, v7, 8, v6
	v_lshl_or_b32 v2, v3, 8, v2
	v_or3_b32 v14, v16, v14, v15
	v_or3_b32 v6, v6, v8, v9
	v_or3_b32 v2, v2, v4, v5
	ds_write2_b32 v84, v14, v10 offset0:192 offset1:196
	ds_write2_b32 v84, v6, v2 offset0:200 offset1:204
